# seam: thread 0 issues its L1 invalidate right behind the XCD-arrival atomic and waits for the atomic alone (vmcnt(1)); last arriver only writes L2 back
# speedup vs baseline: 1.0006x; 1.0006x over previous
; __device__ __forceinline__ unsigned xb_ld(unsigned* p)              { return __hip_atomic_load(p, __ATOMIC_RELAXED, __HIP_MEMORY_SCOPE_AGENT); }
; __device__ __forceinline__ unsigned xb_add(unsigned* p, unsigned v) { return __hip_atomic_fetch_add(p, v, __ATOMIC_RELAXED, __HIP_MEMORY_SCOPE_AGENT); }
; #define XB_SPIN(cond, bar) do { unsigned _sp = 0; while (cond) { __builtin_amdgcn_s_sleep(1); \
;     if ((++_sp & 255u) == 0u) { if (xb_ld(&(bar)[XB_TMO])) break; if (_sp > XB_SPIN_CAP) { atomicAdd(&(bar)[XB_TMO], 1u); break; } } } } while (0)
; __device__ __forceinline__ void xcd_barrier(const XcdBarrier& b) {
;     asm volatile("s_waitcnt vmcnt(0)" ::: "memory");
;     __syncthreads();
;     if (threadIdx.x == 0) {
;         unsigned* bar = b.bar;
;         __builtin_amdgcn_s_waitcnt(0);
;         unsigned nloc = b.st[0], nx = b.st[1];
;         if (nloc == 0u) { xcd_barrier_complete(bar, b.x, nloc, nx); b.st[0] = nloc; b.st[1] = nx; }
;         const unsigned old = xb_add(&bar[XB_XSUB(b.x)], 1u);
;         const unsigned gen = old / nloc;
;         if (old + 1u == (gen + 1u) * nloc) {
;             __builtin_amdgcn_fence(__ATOMIC_RELEASE, "agent");
;             asm volatile("s_waitcnt vmcnt(0)" ::: "memory");
;             const unsigned og = xb_add(&bar[XB_TOP], 1u);
;             const unsigned tg = og / nx;
;             if (og + 1u == (tg + 1u) * nx) xb_add(&bar[XB_TOPGEN], 1u);
;             else XB_SPIN(xb_ld(&bar[XB_TOPGEN]) == tg, bar);
;             __builtin_amdgcn_fence(__ATOMIC_ACQUIRE, "agent");
;             xb_add(&bar[XB_XGEN(b.x)], 1u);
;             asm volatile("s_waitcnt vmcnt(0)" ::: "memory");
;         } else {
;             XB_SPIN(xb_ld(&bar[XB_XGEN(b.x)]) == gen, bar);
;             __builtin_amdgcn_fence(__ATOMIC_ACQUIRE, "agent");
;             asm volatile("s_waitcnt vmcnt(0)" ::: "memory");
;         }
.LBB0_70:
	s_or_b64 exec, exec, s[10:11]
	buffer_inv sc1
	s_waitcnt vmcnt(1)
	v_readfirstlane_b32 s0, v3
	v_add_u32_e32 v5, s0, v1
	v_readlane_b32 s0, v244, 63
	v_add_u32_e32 v3, 1, v5
	v_mov_b32_e32 v1, s0
	v_mad_u32_u24 v2, v1, v2, v2
	s_add_i32 s0, s0, 1
	v_writelane_b32 v244, s0, 63
	v_cmp_ne_u32_e32 vcc, v3, v2
	s_and_saveexec_b64 s[0:1], vcc
	s_xor_b64 s[10:11], exec, s[0:1]
	s_cbranch_execz .LBB0_84
	s_waitcnt lgkmcnt(0)
	v_mad_u32_u24 v3, v1, v0, v0
	v_mov_b32_e32 v0, 0x3400
	global_load_dword v0, v0, s[86:87] sc1
	s_add_u32 s14, s86, 0x3400
	s_addc_u32 s15, s87, 0
	s_waitcnt vmcnt(0)
	v_cmp_lt_u32_e32 vcc, v0, v3
	s_and_saveexec_b64 s[12:13], vcc
	s_cbranch_execz .LBB0_83
	s_mov_b32 s3, 1
	s_mov_b64 s[16:17], 0
	v_mov_b32_e32 v0, 0
	s_branch .LBB0_74

; __device__ __forceinline__ unsigned xb_ld(unsigned* p)              { return __hip_atomic_load(p, __ATOMIC_RELAXED, __HIP_MEMORY_SCOPE_AGENT); }
; __device__ __forceinline__ unsigned xb_add(unsigned* p, unsigned v) { return __hip_atomic_fetch_add(p, v, __ATOMIC_RELAXED, __HIP_MEMORY_SCOPE_AGENT); }
; #define XB_SPIN(cond, bar) do { unsigned _sp = 0; while (cond) { __builtin_amdgcn_s_sleep(1); \
;     if ((++_sp & 255u) == 0u) { if (xb_ld(&(bar)[XB_TMO])) break; if (_sp > XB_SPIN_CAP) { atomicAdd(&(bar)[XB_TMO], 1u); break; } } } } while (0)
; __device__ __forceinline__ void xcd_barrier(const XcdBarrier& b) {
;     ...
;     if (threadIdx.x == 0) {
;         unsigned* bar = b.bar;
;         __builtin_amdgcn_s_waitcnt(0);
;         unsigned nloc = b.st[0], nx = b.st[1];
;         if (nloc == 0u) { xcd_barrier_complete(bar, b.x, nloc, nx); b.st[0] = nloc; b.st[1] = nx; }
;         const unsigned old = xb_add(&bar[XB_XSUB(b.x)], 1u);
;         const unsigned gen = old / nloc;
;         if (old + 1u == (gen + 1u) * nloc) {
;             __builtin_amdgcn_fence(__ATOMIC_RELEASE, "agent");
;             asm volatile("s_waitcnt vmcnt(0)" ::: "memory");
;             const unsigned og = xb_add(&bar[XB_TOP], 1u);
;             const unsigned tg = og / nx;
;             if (og + 1u == (tg + 1u) * nx) xb_add(&bar[XB_TOPGEN], 1u);
;             else XB_SPIN(xb_ld(&bar[XB_TOPGEN]) == tg, bar);
;             __builtin_amdgcn_fence(__ATOMIC_ACQUIRE, "agent");
;             xb_add(&bar[XB_XGEN(b.x)], 1u);
;             asm volatile("s_waitcnt vmcnt(0)" ::: "memory");
;         } else {
;             XB_SPIN(xb_ld(&bar[XB_XGEN(b.x)]) == gen, bar);
;             __builtin_amdgcn_fence(__ATOMIC_ACQUIRE, "agent");
;             asm volatile("s_waitcnt vmcnt(0)" ::: "memory");
;         }
.LBB0_1811:
	s_or_b64 exec, exec, s[8:9]
	buffer_inv sc1
	s_waitcnt vmcnt(1)
	v_readfirstlane_b32 s0, v3
	v_add_u32_e32 v5, s0, v1
	v_readlane_b32 s0, v244, 63
	v_add_u32_e32 v3, 1, v5
	v_mov_b32_e32 v1, s0
	v_mad_u32_u24 v2, v1, v2, v2
	s_add_i32 s0, s0, 1
	v_writelane_b32 v244, s0, 63
	v_cmp_ne_u32_e32 vcc, v3, v2
	s_and_saveexec_b64 s[0:1], vcc
	s_xor_b64 s[8:9], exec, s[0:1]
	s_cbranch_execz .LBB0_1825
	s_waitcnt lgkmcnt(0)
	v_mad_u32_u24 v3, v1, v0, v0
	v_mov_b32_e32 v0, 0x3400
	global_load_dword v0, v0, s[86:87] sc1
	s_add_u32 s12, s86, 0x3400
	s_addc_u32 s13, s87, 0
	s_waitcnt vmcnt(0)
	v_cmp_lt_u32_e32 vcc, v0, v3
	s_and_saveexec_b64 s[10:11], vcc
	s_cbranch_execz .LBB0_1824
	s_mov_b32 s3, 1
	s_mov_b64 s[14:15], 0
	v_mov_b32_e32 v0, 0
	s_branch .LBB0_1815

; __device__ __forceinline__ unsigned xb_ld(unsigned* p)              { return __hip_atomic_load(p, __ATOMIC_RELAXED, __HIP_MEMORY_SCOPE_AGENT); }
; __device__ __forceinline__ unsigned xb_add(unsigned* p, unsigned v) { return __hip_atomic_fetch_add(p, v, __ATOMIC_RELAXED, __HIP_MEMORY_SCOPE_AGENT); }
; #define XB_SPIN(cond, bar) do { unsigned _sp = 0; while (cond) { __builtin_amdgcn_s_sleep(1); \
;     if ((++_sp & 255u) == 0u) { if (xb_ld(&(bar)[XB_TMO])) break; if (_sp > XB_SPIN_CAP) { atomicAdd(&(bar)[XB_TMO], 1u); break; } } } } while (0)
; __device__ __forceinline__ void xcd_barrier(const XcdBarrier& b) {
;     ...
;     if (threadIdx.x == 0) {
;         unsigned* bar = b.bar;
;         __builtin_amdgcn_s_waitcnt(0);
;         unsigned nloc = b.st[0], nx = b.st[1];
;         if (nloc == 0u) { xcd_barrier_complete(bar, b.x, nloc, nx); b.st[0] = nloc; b.st[1] = nx; }
;         const unsigned old = xb_add(&bar[XB_XSUB(b.x)], 1u);
;         const unsigned gen = old / nloc;
;         if (old + 1u == (gen + 1u) * nloc) {
;             __builtin_amdgcn_fence(__ATOMIC_RELEASE, "agent");
;             asm volatile("s_waitcnt vmcnt(0)" ::: "memory");
;             const unsigned og = xb_add(&bar[XB_TOP], 1u);
;             const unsigned tg = og / nx;
;             if (og + 1u == (tg + 1u) * nx) xb_add(&bar[XB_TOPGEN], 1u);
;             else XB_SPIN(xb_ld(&bar[XB_TOPGEN]) == tg, bar);
;             __builtin_amdgcn_fence(__ATOMIC_ACQUIRE, "agent");
;             xb_add(&bar[XB_XGEN(b.x)], 1u);
;             asm volatile("s_waitcnt vmcnt(0)" ::: "memory");
;         } else {
;             XB_SPIN(xb_ld(&bar[XB_XGEN(b.x)]) == gen, bar);
;             __builtin_amdgcn_fence(__ATOMIC_ACQUIRE, "agent");
;             asm volatile("s_waitcnt vmcnt(0)" ::: "memory");
;         }
.LBB0_1936:
	s_or_b64 exec, exec, s[8:9]
	buffer_inv sc1
	s_waitcnt vmcnt(1)
	v_readfirstlane_b32 s0, v3
	v_add_u32_e32 v5, s0, v1
	v_readlane_b32 s0, v244, 63
	v_add_u32_e32 v3, 1, v5
	v_mov_b32_e32 v1, s0
	v_mad_u32_u24 v2, v1, v2, v2
	s_add_i32 s0, s0, 1
	v_writelane_b32 v244, s0, 63
	v_cmp_ne_u32_e32 vcc, v3, v2
	s_and_saveexec_b64 s[0:1], vcc
	s_xor_b64 s[8:9], exec, s[0:1]
	s_cbranch_execz .LBB0_1950
	s_waitcnt lgkmcnt(0)
	v_mad_u32_u24 v3, v1, v0, v0
	v_mov_b32_e32 v0, 0x3400
	global_load_dword v0, v0, s[86:87] sc1
	s_add_u32 s12, s86, 0x3400
	s_addc_u32 s13, s87, 0
	s_waitcnt vmcnt(0)
	v_cmp_lt_u32_e32 vcc, v0, v3
	s_and_saveexec_b64 s[10:11], vcc
	s_cbranch_execz .LBB0_1949
	s_mov_b32 s22, 1
	s_mov_b64 s[14:15], 0
	v_mov_b32_e32 v0, 0
	s_branch .LBB0_1940
